# phase 0 W_in transpose tile: the 16 per-thread weight loads are issued back to back under one exec mask with counted vmcnt waits instead of one load + vmcnt(0) at a time
# speedup vs baseline: 1.0249x; 1.0158x over previous
; DI bf16_t f2bf(float a) { return (bf16_t)(pk2(a, 0.f) & 0xffffu); }
; DI int win_src_col(int n) {
;     if (n < 832) return n;
;     if (n < 848) return 4928 + (n - 832);
;     if (n < 896) return -1;
;     if (n < 1920) return 832 + (n - 896);
;     if (n < 2944) return 4944 + (n - 1920);
;     if (n < 6016) return 1856 + (n - 2944);
;     return -1;
; }
; template <int MODE>
; DI void transpose_tile(const float* __restrict__ W, int K, int Nsrc, bf16_t* __restrict__ WT, int ldo, const float* __restrict__ gain, int k0, int n0,
;                        unsigned char* smem, int tid) {
;     bf16_t* t = (bf16_t*)smem;
; #pragma unroll 4
;     for (int i = 0; i < 16; ++i) {
;         const int e = tid + 256 * i, kk = e >> 6, nn = e & 63;
;         const int src = MODE == 0 ? win_src_col(n0 + nn) : (n0 + nn);
;         float v = src >= 0 ? W[(size_t)(k0 + kk) * Nsrc + src] : 0.f;
;         if (gain) v *= gain[k0 + kk];
;         t[nn * 66 + kk] = f2bf(v);
;     }
.LBB0_61:
	s_mul_hi_i32 s0, s35, 0x2aaaaaab
	s_lshr_b32 s1, s0, 31
	s_ashr_i32 s0, s0, 4
	s_add_i32 s0, s0, s1
	s_lshl_b32 s20, s0, 6
	s_mulk_i32 s0, 0x60
	s_sub_i32 s0, s35, s0
	s_lshl_b32 s36, s0, 6
	v_and_b32_e32 v1, 63, v6
	v_or_b32_e32 v3, s36, v1
	s_cmpk_lt_u32 s36, 0x380
	v_or_b32_e32 v4, 0x1000, v3
	v_cmp_gt_u32_e32 vcc, s31, v3
	v_add_u32_e32 v9, 0xfffffbc0, v3
	v_add_u32_e32 v8, 0xbd0, v3
	v_cndmask_b32_e32 v4, -1, v4, vcc
	s_cselect_b64 vcc, -1, 0
	s_cmpk_lt_u32 s36, 0x780
	s_cselect_b64 s[0:1], -1, 0
	s_cmpk_lt_u32 s36, 0xb80
	s_cselect_b64 s[4:5], -1, 0
	s_cmpk_lt_u32 s36, 0x1780
	s_cselect_b64 s[6:7], -1, 0
	v_cndmask_b32_e64 v9, -1, v9, s[6:7]
	v_subrev_u32_e32 v7, 64, v3
	v_cndmask_b32_e64 v8, v9, v8, s[4:5]
	v_cndmask_b32_e64 v7, v8, v7, s[0:1]
	v_cndmask_b32_e32 v4, v7, v4, vcc
	v_cmp_gt_i32_e32 vcc, s30, v3
	s_mov_b32 s4, 0
	s_nop 0
	v_cndmask_b32_e32 v4, v4, v3, vcc
	v_mov_b32_e32 v3, s10
	v_cmp_lt_i32_e32 vcc, -1, v4
	v_lshl_add_u64 v[8:9], v[4:5], 2, s[46:47]
	v_mad_u32_u24 v1, v1, s27, v3
	v_lshrrev_b32_e32 v3, 6, v6
	v_add_u32_e32 v7, s20, v3
	v_mad_i64_i32 v[10:11], s[6:7], v7, s34, v[8:9]
	v_lshl_add_u32 v1, v3, 1, v1
	s_mov_b32 s0, 0x17500
	s_mov_b32 s1, 0
	v_mov_b32_e32 v12, 0
	v_mov_b32_e32 v13, 0
	v_mov_b32_e32 v14, 0
	v_mov_b32_e32 v15, 0
	v_mov_b32_e32 v16, 0
	v_mov_b32_e32 v17, 0
	v_mov_b32_e32 v18, 0
	v_mov_b32_e32 v19, 0
	v_mov_b32_e32 v20, 0
	v_mov_b32_e32 v21, 0
	v_mov_b32_e32 v22, 0
	v_mov_b32_e32 v23, 0
	v_mov_b32_e32 v24, 0
	v_mov_b32_e32 v25, 0
	v_mov_b32_e32 v26, 0
	v_mov_b32_e32 v27, 0
	s_and_saveexec_b64 s[4:5], vcc
	global_load_dword v12, v[10:11], off
	v_lshl_add_u64 v[10:11], v[10:11], 0, s[0:1]
	global_load_dword v13, v[10:11], off
	v_lshl_add_u64 v[10:11], v[10:11], 0, s[0:1]
	global_load_dword v14, v[10:11], off
	v_lshl_add_u64 v[10:11], v[10:11], 0, s[0:1]
	global_load_dword v15, v[10:11], off
	v_lshl_add_u64 v[10:11], v[10:11], 0, s[0:1]
	global_load_dword v16, v[10:11], off
	v_lshl_add_u64 v[10:11], v[10:11], 0, s[0:1]
	global_load_dword v17, v[10:11], off
	v_lshl_add_u64 v[10:11], v[10:11], 0, s[0:1]
	global_load_dword v18, v[10:11], off
	v_lshl_add_u64 v[10:11], v[10:11], 0, s[0:1]
	global_load_dword v19, v[10:11], off
	v_lshl_add_u64 v[10:11], v[10:11], 0, s[0:1]
	global_load_dword v20, v[10:11], off
	v_lshl_add_u64 v[10:11], v[10:11], 0, s[0:1]
	global_load_dword v21, v[10:11], off
	v_lshl_add_u64 v[10:11], v[10:11], 0, s[0:1]
	global_load_dword v22, v[10:11], off
	v_lshl_add_u64 v[10:11], v[10:11], 0, s[0:1]
	global_load_dword v23, v[10:11], off
	v_lshl_add_u64 v[10:11], v[10:11], 0, s[0:1]
	global_load_dword v24, v[10:11], off
	v_lshl_add_u64 v[10:11], v[10:11], 0, s[0:1]
	global_load_dword v25, v[10:11], off
	v_lshl_add_u64 v[10:11], v[10:11], 0, s[0:1]
	global_load_dword v26, v[10:11], off
	v_lshl_add_u64 v[10:11], v[10:11], 0, s[0:1]
	global_load_dword v27, v[10:11], off
	s_or_b64 exec, exec, s[4:5]
	s_waitcnt vmcnt(14)
	v_cvt_pk_bf16_f32 v12, v12, v13
	ds_write_b16 v1, v12
	ds_write_b16_d16_hi v1, v12 offset:8
	s_waitcnt vmcnt(12)
	v_cvt_pk_bf16_f32 v14, v14, v15
	ds_write_b16 v1, v14 offset:16
	ds_write_b16_d16_hi v1, v14 offset:24
	s_waitcnt vmcnt(10)
	v_cvt_pk_bf16_f32 v16, v16, v17
	ds_write_b16 v1, v16 offset:32
	ds_write_b16_d16_hi v1, v16 offset:40
	s_waitcnt vmcnt(8)
	v_cvt_pk_bf16_f32 v18, v18, v19
	ds_write_b16 v1, v18 offset:48
	ds_write_b16_d16_hi v1, v18 offset:56
	s_waitcnt vmcnt(6)
	v_cvt_pk_bf16_f32 v20, v20, v21
	ds_write_b16 v1, v20 offset:64
	ds_write_b16_d16_hi v1, v20 offset:72
	s_waitcnt vmcnt(4)
	v_cvt_pk_bf16_f32 v22, v22, v23
	ds_write_b16 v1, v22 offset:80
	ds_write_b16_d16_hi v1, v22 offset:88
	s_waitcnt vmcnt(2)
	v_cvt_pk_bf16_f32 v24, v24, v25
	ds_write_b16 v1, v24 offset:96
	ds_write_b16_d16_hi v1, v24 offset:104
	s_waitcnt vmcnt(0)
	v_cvt_pk_bf16_f32 v26, v26, v27
	ds_write_b16 v1, v26 offset:112
	ds_write_b16_d16_hi v1, v26 offset:120
	s_branch .LBB0_26
